# attention: tile-A row-sum packed adds split into plain adds, V-read LDS base adds folded into ds_read offsets
# baseline (speedup 1.0000x reference)
; #define MFMA(a, b, c) __builtin_amdgcn_mfma_f32_32x32x16_f16((a), (b), (c), 0, 0, 0)
; template <int DK, bool MLA>
; DI void attn_item(const h16* __restrict__ Q, const h16* __restrict__ Kp, const h16* __restrict__ Kr, const h16* __restrict__ Vt,
;                   int kbeg, int kend, h16* __restrict__ out, h16* sm) {
;     ...
;     float ps = 0.f;
; #pragma unroll
;     for (int i = 0; i < 16; ++i) {
;       st[0][i] = __builtin_amdgcn_exp2f(st[0][i]);
;       st[1][i] = __builtin_amdgcn_exp2f(st[1][i]);
;       ps += st[0][i] + st[1][i];
;     }
;     lsum += ps;
; #pragma unroll
;     for (int s4 = 0; s4 < 4; ++s4) {
;       const int kt2 = s4 >> 1, hf = s4 & 1;
;       h16x8 pb;
; #pragma unroll
;       for (int j = 0; j < 8; ++j) pb[j] = (h16)st[kt2][8 * hf + j];
;       const int kb = kt2 * 32 + 16 * hf;
; #pragma unroll
;       for (int dt = 0; dt < 2; ++dt) {
;         const h16* vp = vsm + (dt * 32 + r) * 72 + kb + 4 * hh;
;         h16x4 lo = *(const h16x4*)vp, hi = *(const h16x4*)(vp + 8);
;         h16x8 va = __builtin_shufflevector(lo, hi, 0, 1, 2, 3, 4, 5, 6, 7);
;         ot[dt] = MFMA(va, pb, ot[dt]);
;       }
;     }
.LBB0_2734:
	v_exp_f32_e32 v152, v64
	v_exp_f32_e32 v154, v48
	v_exp_f32_e32 v155, v65
	v_exp_f32_e32 v156, v49
	v_exp_f32_e32 v157, v66
	v_exp_f32_e32 v158, v50
	v_exp_f32_e32 v159, v67
	v_exp_f32_e32 v160, v51
	v_add_f32_e32 v2, v154, v152
	v_exp_f32_e32 v161, v68
	v_exp_f32_e32 v162, v52
	v_add_f32_e32 v2, 0, v2
	v_add_f32_e32 v3, v156, v155
	v_exp_f32_e32 v14, v69
	v_exp_f32_e32 v6, v53
	v_add_f32_e32 v2, v3, v2
	v_add_f32_e32 v3, v158, v157
	v_add_f32_e32 v2, v3, v2
	v_add_f32_e32 v3, v160, v159
	v_add_f32_e32 v15, v3, v2
	v_add_f32_e32 v7, v162, v161
	v_add_f32_e32 v2, v6, v14
	v_add_f32_e32 v3, v7, v15
	v_exp_f32_e32 v7, v70
	v_add_f32_e32 v49, v2, v3
	v_exp_f32_e32 v15, v54
	v_exp_f32_e32 v48, v71
	v_exp_f32_e32 v12, v55
	v_exp_f32_e32 v70, v56
	v_add_f32_e32 v13, v15, v7
	v_exp_f32_e32 v62, v62
	v_add_f32_e32 v2, v12, v48
	v_add_f32_e32 v3, v13, v49
	v_exp_f32_e32 v13, v72
	v_add_f32_e32 v65, v2, v3
	v_exp_f32_e32 v64, v73
	v_exp_f32_e32 v2, v57
	v_add_f32_e32 v3, v70, v13
	v_cvt_pk_f16_f32 v49, v157, v159
	v_cvt_pk_f16_f32 v15, v15, v12
	v_add_f32_e32 v4, v2, v64
	v_add_f32_e32 v5, v3, v65
	v_exp_f32_e32 v3, v74
	v_add_f32_e32 v67, v4, v5
	v_exp_f32_e32 v65, v58
	v_exp_f32_e32 v66, v75
	v_exp_f32_e32 v4, v59
	v_cvt_pk_f16_f32 v12, v154, v156
	v_add_f32_e32 v5, v65, v3
	s_addk_i32 s6, 0x80
	v_add_f32_e32 v8, v4, v66
	v_add_f32_e32 v9, v5, v67
	v_exp_f32_e32 v5, v76
	v_add_f32_e32 v69, v8, v9
	v_exp_f32_e32 v67, v60
	v_exp_f32_e32 v68, v77
	v_exp_f32_e32 v8, v61
	s_add_i32 s9, s9, 2
	v_add_f32_e32 v9, v67, v5
	s_cmp_lt_u32 s38, s8
	v_add_f32_e32 v10, v8, v68
	v_add_f32_e32 v11, v9, v69
	v_exp_f32_e32 v9, v78
	v_add_f32_e32 v61, v10, v11
	v_exp_f32_e32 v60, v79
	v_exp_f32_e32 v10, v63
	v_add_f32_e32 v11, v62, v9
	v_add_f32_e32 v50, v10, v60
	v_add_f32_e32 v51, v11, v61
	s_nop 0
	v_add_f32_e32 v11, v50, v51
	v_add_f32_e32 v153, v0, v11
	ds_read_b128 v[52:55], v143 offset:27648
	ds_read_b128 v[56:59], v143 offset:27680
	v_cvt_pk_f16_f32 v51, v7, v48
	v_cvt_pk_f16_f32 v50, v161, v14
	v_cvt_pk_f16_f32 v48, v152, v155
	v_cvt_pk_f16_f32 v14, v162, v6
	s_waitcnt lgkmcnt(1)
	v_mfma_f32_32x32x16_f16 v[32:47], v[52:55], v[48:51], v[32:47]
	ds_read_b128 v[52:55], v143 offset:32256
	v_cvt_pk_f16_f32 v7, v62, v10
	v_cvt_pk_f16_f32 v6, v67, v8
	s_waitcnt lgkmcnt(0)
	v_mfma_f32_32x32x16_f16 v[16:31], v[52:55], v[48:51], v[16:31]
	ds_read_b128 v[52:55], v143 offset:32288
	v_cvt_pk_f16_f32 v51, v9, v60
	v_cvt_pk_f16_f32 v50, v5, v68
	v_cvt_pk_f16_f32 v49, v3, v66
	v_cvt_pk_f16_f32 v48, v13, v64
	v_cvt_pk_f16_f32 v13, v158, v160
	ds_read_b128 v[8:11], v143 offset:27744
	v_mfma_f32_32x32x16_f16 v[32:47], v[56:59], v[48:51], v[32:47]
	v_cvt_pk_f16_f32 v5, v65, v4
	v_cvt_pk_f16_f32 v4, v70, v2
	s_waitcnt lgkmcnt(1)
	v_mfma_f32_32x32x16_f16 v[16:31], v[52:55], v[48:51], v[16:31]
	ds_read_b128 v[48:51], v143 offset:27712
	s_waitcnt lgkmcnt(0)
	v_mfma_f32_32x32x16_f16 v[32:47], v[48:51], v[12:15], v[32:47]
	ds_read_b128 v[48:51], v143 offset:32320
	v_mfma_f32_32x32x16_f16 v[32:47], v[8:11], v[4:7], v[32:47]
	ds_read_b128 v[8:11], v143 offset:32352
	s_waitcnt lgkmcnt(1)
	v_mfma_f32_32x32x16_f16 v[16:31], v[48:51], v[12:15], v[16:31]
	s_waitcnt lgkmcnt(0)
	v_mfma_f32_32x32x16_f16 v[16:31], v[8:11], v[4:7], v[16:31]
	s_cbranch_scc0 .LBB0_2743

; #define MFMA(a, b, c) __builtin_amdgcn_mfma_f32_32x32x16_f16((a), (b), (c), 0, 0, 0)
; template <int DK, bool MLA>
; DI void attn_item(const h16* __restrict__ Q, const h16* __restrict__ Kp, const h16* __restrict__ Kr, const h16* __restrict__ Vt,
;                   int kbeg, int kend, h16* __restrict__ out, h16* sm) {
;     ...
; #pragma unroll
;     for (int i = 0; i < NCH; ++i) {
;       const int c = tid + 256 * i, key = c / NKC, part = c % NKC;
;       *(u32x4*)(ksm + key * KS + part * 8) = RK[i];
;     }
; #pragma unroll
;     for (int i = 0; i < 2; ++i) {
;       const int c = tid + 256 * i, dv = c >> 3, kc = c & 7;
;       *(u32x4*)(vsm + dv * 72 + kc * 8) = RV[i];
;     }
;     __syncthreads();
;     if (it + 2 < ntile) ATT_GLOAD(RK, RV, kbeg + (it + 2) * 64)
;     ...
;     float ps = 0.f;
; #pragma unroll
;     for (int i = 0; i < 16; ++i) {
;       st[0][i] = __builtin_amdgcn_exp2f(st[0][i]);
;       st[1][i] = __builtin_amdgcn_exp2f(st[1][i]);
;       ps += st[0][i] + st[1][i];
;     }
;     lsum += ps;
; #pragma unroll
;     for (int s4 = 0; s4 < 4; ++s4) {
;       const int kt2 = s4 >> 1, hf = s4 & 1;
;       h16x8 pb;
; #pragma unroll
;       for (int j = 0; j < 8; ++j) pb[j] = (h16)st[kt2][8 * hf + j];
;       const int kb = kt2 * 32 + 16 * hf;
; #pragma unroll
;       for (int dt = 0; dt < 2; ++dt) {
;         const h16* vp = vsm + (dt * 32 + r) * 72 + kb + 4 * hh;
;         h16x4 lo = *(const h16x4*)vp, hi = *(const h16x4*)(vp + 8);
;         h16x8 va = __builtin_shufflevector(lo, hi, 0, 1, 2, 3, 4, 5, 6, 7);
;         ot[dt] = MFMA(va, pb, ot[dt]);
;       }
;     }
.LBB0_2739:
	v_exp_f32_e32 v166, v64
	v_exp_f32_e32 v13, v65
	v_exp_f32_e32 v15, v66
	v_exp_f32_e32 v152, v67
	v_exp_f32_e32 v156, v68
	v_exp_f32_e32 v157, v69
	v_exp_f32_e32 v168, v70
	v_exp_f32_e32 v160, v71
	v_exp_f32_e32 v12, v60
	v_exp_f32_e32 v158, v52
	v_exp_f32_e32 v159, v53
	v_exp_f32_e32 v169, v54
	v_exp_f32_e32 v163, v55
	v_exp_f32_e32 v164, v56
	v_exp_f32_e32 v165, v57
	v_exp_f32_e32 v10, v58
	v_exp_f32_e32 v11, v59
	ds_read_b128 v[52:55], v143 offset:9216
	ds_read_b128 v[56:59], v143 offset:9248
	v_exp_f32_e32 v167, v48
	v_exp_f32_e32 v14, v49
	v_exp_f32_e32 v154, v50
	v_exp_f32_e32 v155, v51
	v_exp_f32_e32 v4, v61
	v_cvt_pk_f16_f32 v51, v168, v160
	v_cvt_pk_f16_f32 v50, v156, v157
	v_cvt_pk_f16_f32 v49, v15, v152
	v_cvt_pk_f16_f32 v48, v166, v13
	v_exp_f32_e32 v161, v72
	s_waitcnt lgkmcnt(1)
	v_mfma_f32_32x32x16_f16 v[32:47], v[52:55], v[48:51], v[32:47]
	ds_read_b128 v[52:55], v143 offset:13824
	v_exp_f32_e32 v162, v73
	v_exp_f32_e32 v7, v74
	v_exp_f32_e32 v8, v75
	v_exp_f32_e32 v9, v76
	v_exp_f32_e32 v0, v77
	v_exp_f32_e32 v2, v78
	s_waitcnt lgkmcnt(0)
	v_mfma_f32_32x32x16_f16 v[16:31], v[52:55], v[48:51], v[16:31]
	ds_read_b128 v[52:55], v143 offset:13856
	v_exp_f32_e32 v3, v79
	v_cvt_pk_f16_f32 v50, v9, v0
	v_cvt_pk_f16_f32 v49, v7, v8
	v_cvt_pk_f16_f32 v48, v161, v162
	v_cvt_pk_f16_f32 v51, v2, v3
	v_exp_f32_e32 v5, v62
	v_exp_f32_e32 v6, v63
	s_waitcnt lgkmcnt(0)
	v_mfma_f32_32x32x16_f16 v[16:31], v[52:55], v[48:51], v[16:31]
	ds_read_b128 v[52:55], v143 offset:9280
	s_cmp_ge_u32 s9, s8
	v_mfma_f32_32x32x16_f16 v[32:47], v[56:59], v[48:51], v[32:47]
	v_cvt_pk_f16_f32 v51, v169, v163
	v_cvt_pk_f16_f32 v50, v158, v159
	v_cvt_pk_f16_f32 v49, v154, v155
	v_cvt_pk_f16_f32 v48, v167, v14
	s_waitcnt lgkmcnt(0)
	s_nop 0
	v_mfma_f32_32x32x16_f16 v[32:47], v[52:55], v[48:51], v[32:47]
	ds_read_b128 v[52:55], v143 offset:13888
	s_waitcnt lgkmcnt(0)
	v_mfma_f32_32x32x16_f16 v[16:31], v[52:55], v[48:51], v[16:31]
	ds_read_b128 v[52:55], v143 offset:9312
	v_cvt_pk_f16_f32 v51, v5, v6
	v_cvt_pk_f16_f32 v50, v12, v4
	v_cvt_pk_f16_f32 v49, v10, v11
	v_cvt_pk_f16_f32 v48, v164, v165
	s_waitcnt lgkmcnt(0)
	s_nop 0
	v_mfma_f32_32x32x16_f16 v[32:47], v[52:55], v[48:51], v[32:47]
	ds_read_b128 v[52:55], v143 offset:13920
	ds_write_b128 v129, v[100:103] offset:18432
	ds_write_b128 v131, v[96:99] offset:18432
	ds_write_b128 v140, v[108:111] offset:27648
	ds_write_b128 v142, v[104:107] offset:27648
	s_waitcnt lgkmcnt(0)
	s_barrier
	v_mfma_f32_32x32x16_f16 v[16:31], v[52:55], v[48:51], v[16:31]
	s_cbranch_scc1 .LBB0_2741
	s_ashr_i32 s7, s6, 31
	s_lshl_b64 s[40:41], s[6:7], 1
	global_load_dwordx4 v[100:103], v[220:221], off
	global_load_dwordx4 v[96:99], v[222:223], off
	v_lshl_add_u64 v[48:49], v[134:135], 0, s[40:41]
	v_lshl_add_u64 v[50:51], v[132:133], 0, s[40:41]
	global_load_dwordx4 v[108:111], v[48:49], off
	global_load_dwordx4 v[104:107], v[50:51], off
	v_lshl_add_u64 v[220:221], v[220:221], 0, v[228:229]
	v_lshl_add_u64 v[222:223], v[222:223], 0, v[228:229]

; #define MFMA(a, b, c) __builtin_amdgcn_mfma_f32_32x32x16_f16((a), (b), (c), 0, 0, 0)
; template <int DK, bool MLA>
; DI void attn_item(const h16* __restrict__ Q, const h16* __restrict__ Kp, const h16* __restrict__ Kr, const h16* __restrict__ Vt,
;                   int kbeg, int kend, h16* __restrict__ out, h16* sm) {
;     ...
;     float ps = 0.f;
; #pragma unroll
;     for (int i = 0; i < 16; ++i) {
;       st[0][i] = __builtin_amdgcn_exp2f(st[0][i]);
;       st[1][i] = __builtin_amdgcn_exp2f(st[1][i]);
;       ps += st[0][i] + st[1][i];
;     }
;     lsum += ps;
; #pragma unroll
;     for (int s4 = 0; s4 < 4; ++s4) {
;       const int kt2 = s4 >> 1, hf = s4 & 1;
;       h16x8 pb;
; #pragma unroll
;       for (int j = 0; j < 8; ++j) pb[j] = (h16)st[kt2][8 * hf + j];
;       const int kb = kt2 * 32 + 16 * hf;
; #pragma unroll
;       for (int dt = 0; dt < 2; ++dt) {
;         const h16* vp = vsm + (dt * 32 + r) * 72 + kb + 4 * hh;
;         h16x4 lo = *(const h16x4*)vp, hi = *(const h16x4*)(vp + 8);
;         h16x8 va = __builtin_shufflevector(lo, hi, 0, 1, 2, 3, 4, 5, 6, 7);
;         ot[dt] = MFMA(va, pb, ot[dt]);
;       }
;     }
.LBB0_2770:
	v_exp_f32_e32 v179, v64
	v_exp_f32_e32 v180, v48
	v_exp_f32_e32 v181, v65
	v_exp_f32_e32 v182, v49
	v_exp_f32_e32 v183, v66
	v_exp_f32_e32 v184, v50
	v_exp_f32_e32 v185, v67
	v_exp_f32_e32 v186, v51
	v_add_f32_e32 v2, v180, v179
	v_exp_f32_e32 v187, v68
	v_exp_f32_e32 v188, v52
	v_add_f32_e32 v2, 0, v2
	v_add_f32_e32 v3, v182, v181
	v_exp_f32_e32 v14, v69
	v_exp_f32_e32 v6, v53
	v_add_f32_e32 v2, v3, v2
	v_add_f32_e32 v3, v184, v183
	v_add_f32_e32 v2, v3, v2
	v_add_f32_e32 v3, v186, v185
	v_add_f32_e32 v15, v3, v2
	v_add_f32_e32 v7, v188, v187
	v_add_f32_e32 v2, v6, v14
	v_add_f32_e32 v3, v7, v15
	v_exp_f32_e32 v7, v70
	v_add_f32_e32 v49, v2, v3
	v_exp_f32_e32 v15, v54
	v_exp_f32_e32 v48, v71
	v_exp_f32_e32 v12, v55
	v_exp_f32_e32 v70, v56
	v_add_f32_e32 v13, v15, v7
	v_exp_f32_e32 v62, v62
	v_add_f32_e32 v2, v12, v48
	v_add_f32_e32 v3, v13, v49
	v_exp_f32_e32 v13, v72
	v_add_f32_e32 v65, v2, v3
	v_exp_f32_e32 v64, v73
	v_exp_f32_e32 v2, v57
	v_add_f32_e32 v3, v70, v13
	v_cvt_pk_f16_f32 v49, v183, v185
	v_cvt_pk_f16_f32 v15, v15, v12
	v_add_f32_e32 v4, v2, v64
	v_add_f32_e32 v5, v3, v65
	v_exp_f32_e32 v3, v74
	v_add_f32_e32 v67, v4, v5
	v_exp_f32_e32 v65, v58
	v_exp_f32_e32 v66, v75
	v_exp_f32_e32 v4, v59
	v_cvt_pk_f16_f32 v12, v180, v182
	v_add_f32_e32 v5, v65, v3
	s_addk_i32 s6, 0x80
	v_add_f32_e32 v8, v4, v66
	v_add_f32_e32 v9, v5, v67
	v_exp_f32_e32 v5, v76
	v_add_f32_e32 v69, v8, v9
	v_exp_f32_e32 v67, v60
	v_exp_f32_e32 v68, v77
	v_exp_f32_e32 v8, v61
	s_add_i32 s9, s9, 2
	v_add_f32_e32 v9, v67, v5
	s_cmp_lt_u32 s10, s8
	v_add_f32_e32 v10, v8, v68
	v_add_f32_e32 v11, v9, v69
	v_exp_f32_e32 v9, v78
	v_add_f32_e32 v61, v10, v11
	v_exp_f32_e32 v60, v79
	v_exp_f32_e32 v10, v63
	v_add_f32_e32 v11, v62, v9
	v_add_f32_e32 v50, v10, v60
	v_add_f32_e32 v51, v11, v61
	s_nop 0
	v_add_f32_e32 v11, v50, v51
	v_add_f32_e32 v153, v0, v11
	ds_read_b128 v[52:55], v165 offset:35840
	ds_read_b128 v[56:59], v165 offset:35872
	v_cvt_pk_f16_f32 v51, v7, v48
	v_cvt_pk_f16_f32 v50, v187, v14
	v_cvt_pk_f16_f32 v48, v179, v181
	v_cvt_pk_f16_f32 v14, v188, v6
	s_waitcnt lgkmcnt(1)
	v_mfma_f32_32x32x16_f16 v[32:47], v[52:55], v[48:51], v[32:47]
	ds_read_b128 v[52:55], v165 offset:40448
	v_cvt_pk_f16_f32 v7, v62, v10
	v_cvt_pk_f16_f32 v6, v67, v8
	s_waitcnt lgkmcnt(0)
	v_mfma_f32_32x32x16_f16 v[16:31], v[52:55], v[48:51], v[16:31]
	ds_read_b128 v[52:55], v165 offset:40480
	v_cvt_pk_f16_f32 v51, v9, v60
	v_cvt_pk_f16_f32 v50, v5, v68
	v_cvt_pk_f16_f32 v49, v3, v66
	v_cvt_pk_f16_f32 v48, v13, v64
	v_cvt_pk_f16_f32 v13, v184, v186
	ds_read_b128 v[8:11], v165 offset:35936
	v_mfma_f32_32x32x16_f16 v[32:47], v[56:59], v[48:51], v[32:47]
	v_cvt_pk_f16_f32 v5, v65, v4
	v_cvt_pk_f16_f32 v4, v70, v2
	s_waitcnt lgkmcnt(1)
	v_mfma_f32_32x32x16_f16 v[16:31], v[52:55], v[48:51], v[16:31]
	ds_read_b128 v[48:51], v165 offset:35904
	s_waitcnt lgkmcnt(0)
	v_mfma_f32_32x32x16_f16 v[32:47], v[48:51], v[12:15], v[32:47]
	ds_read_b128 v[48:51], v165 offset:40512
	v_mfma_f32_32x32x16_f16 v[32:47], v[8:11], v[4:7], v[32:47]
	ds_read_b128 v[8:11], v165 offset:40544
	s_waitcnt lgkmcnt(1)
	v_mfma_f32_32x32x16_f16 v[16:31], v[48:51], v[12:15], v[16:31]
	s_waitcnt lgkmcnt(0)
	v_mfma_f32_32x32x16_f16 v[16:31], v[8:11], v[4:7], v[16:31]
	s_cbranch_scc0 .LBB0_2720

; #define MFMA(a, b, c) __builtin_amdgcn_mfma_f32_32x32x16_f16((a), (b), (c), 0, 0, 0)
; template <int DK, bool MLA>
; DI void attn_item(const h16* __restrict__ Q, const h16* __restrict__ Kp, const h16* __restrict__ Kr, const h16* __restrict__ Vt,
;                   int kbeg, int kend, h16* __restrict__ out, h16* sm) {
;     ...
; #pragma unroll
;     for (int i = 0; i < NCH; ++i) {
;       const int c = tid + 256 * i, key = c / NKC, part = c % NKC;
;       *(u32x4*)(ksm + key * KS + part * 8) = RK[i];
;     }
; #pragma unroll
;     for (int i = 0; i < 2; ++i) {
;       const int c = tid + 256 * i, dv = c >> 3, kc = c & 7;
;       *(u32x4*)(vsm + dv * 72 + kc * 8) = RV[i];
;     }
;     __syncthreads();
;     if (it + 2 < ntile) ATT_GLOAD(RK, RV, kbeg + (it + 2) * 64)
;     ...
;     float ps = 0.f;
; #pragma unroll
;     for (int i = 0; i < 16; ++i) {
;       st[0][i] = __builtin_amdgcn_exp2f(st[0][i]);
;       st[1][i] = __builtin_amdgcn_exp2f(st[1][i]);
;       ps += st[0][i] + st[1][i];
;     }
;     lsum += ps;
; #pragma unroll
;     for (int s4 = 0; s4 < 4; ++s4) {
;       const int kt2 = s4 >> 1, hf = s4 & 1;
;       h16x8 pb;
; #pragma unroll
;       for (int j = 0; j < 8; ++j) pb[j] = (h16)st[kt2][8 * hf + j];
;       const int kb = kt2 * 32 + 16 * hf;
; #pragma unroll
;       for (int dt = 0; dt < 2; ++dt) {
;         const h16* vp = vsm + (dt * 32 + r) * 72 + kb + 4 * hh;
;         h16x4 lo = *(const h16x4*)vp, hi = *(const h16x4*)(vp + 8);
;         h16x8 va = __builtin_shufflevector(lo, hi, 0, 1, 2, 3, 4, 5, 6, 7);
;         ot[dt] = MFMA(va, pb, ot[dt]);
;       }
;     }
.LBB0_2775:
	v_exp_f32_e32 v192, v64
	v_exp_f32_e32 v193, v65
	v_exp_f32_e32 v5, v66
	v_exp_f32_e32 v6, v67
	v_exp_f32_e32 v186, v68
	v_exp_f32_e32 v9, v69
	v_exp_f32_e32 v188, v70
	v_exp_f32_e32 v189, v71
	v_exp_f32_e32 v15, v60
	v_exp_f32_e32 v187, v52
	v_exp_f32_e32 v13, v53
	v_exp_f32_e32 v190, v54
	v_exp_f32_e32 v191, v55
	v_exp_f32_e32 v183, v56
	v_exp_f32_e32 v184, v57
	v_exp_f32_e32 v185, v58
	v_exp_f32_e32 v14, v59
	ds_read_b128 v[52:55], v165 offset:13312
	ds_read_b128 v[56:59], v165 offset:13344
	v_exp_f32_e32 v194, v48
	v_exp_f32_e32 v195, v49
	v_exp_f32_e32 v7, v50
	v_exp_f32_e32 v8, v51
	v_exp_f32_e32 v179, v61
	v_cvt_pk_f16_f32 v51, v188, v189
	v_cvt_pk_f16_f32 v50, v186, v9
	v_cvt_pk_f16_f32 v49, v5, v6
	v_cvt_pk_f16_f32 v48, v192, v193
	v_exp_f32_e32 v180, v72
	s_waitcnt lgkmcnt(1)
	v_mfma_f32_32x32x16_f16 v[32:47], v[52:55], v[48:51], v[32:47]
	ds_read_b128 v[52:55], v165 offset:17920
	v_exp_f32_e32 v181, v73
	v_exp_f32_e32 v182, v74
	v_exp_f32_e32 v10, v75
	v_exp_f32_e32 v11, v76
	v_exp_f32_e32 v12, v77
	v_exp_f32_e32 v0, v78
	s_waitcnt lgkmcnt(0)
	v_mfma_f32_32x32x16_f16 v[16:31], v[52:55], v[48:51], v[16:31]
	ds_read_b128 v[52:55], v165 offset:17952
	v_exp_f32_e32 v2, v79
	v_cvt_pk_f16_f32 v50, v11, v12
	v_cvt_pk_f16_f32 v49, v182, v10
	v_cvt_pk_f16_f32 v48, v180, v181
	v_cvt_pk_f16_f32 v51, v0, v2
	v_exp_f32_e32 v3, v62
	v_exp_f32_e32 v4, v63
	s_waitcnt lgkmcnt(0)
	v_mfma_f32_32x32x16_f16 v[16:31], v[52:55], v[48:51], v[16:31]
	ds_read_b128 v[52:55], v165 offset:13376
	s_cmp_ge_u32 s9, s8
	v_mfma_f32_32x32x16_f16 v[32:47], v[56:59], v[48:51], v[32:47]
	v_cvt_pk_f16_f32 v51, v190, v191
	v_cvt_pk_f16_f32 v50, v187, v13
	v_cvt_pk_f16_f32 v49, v7, v8
	v_cvt_pk_f16_f32 v48, v194, v195
	s_waitcnt lgkmcnt(0)
	s_nop 0
	v_mfma_f32_32x32x16_f16 v[32:47], v[52:55], v[48:51], v[32:47]
	ds_read_b128 v[52:55], v165 offset:17984
	s_waitcnt lgkmcnt(0)
	v_mfma_f32_32x32x16_f16 v[16:31], v[52:55], v[48:51], v[16:31]
	ds_read_b128 v[52:55], v165 offset:13408
	v_cvt_pk_f16_f32 v51, v3, v4
	v_cvt_pk_f16_f32 v50, v15, v179
	v_cvt_pk_f16_f32 v49, v185, v14
	v_cvt_pk_f16_f32 v48, v183, v184
	s_waitcnt lgkmcnt(0)
	s_nop 0
	v_mfma_f32_32x32x16_f16 v[32:47], v[52:55], v[48:51], v[32:47]
	ds_read_b128 v[52:55], v165 offset:18016
	s_waitcnt vmcnt(4)
	ds_write_b128 v147, v[124:127] offset:22528
	s_waitcnt vmcnt(3)
	ds_write_b128 v149, v[128:131] offset:22528
	s_waitcnt vmcnt(2)
	ds_write_b128 v151, v[132:135] offset:22528
	s_waitcnt vmcnt(0)
	ds_write_b128 v162, v[140:143] offset:35840
	ds_write_b128 v164, v[136:139] offset:35840
	s_waitcnt lgkmcnt(0)
	s_barrier
	v_mfma_f32_32x32x16_f16 v[16:31], v[52:55], v[48:51], v[16:31]
	s_cbranch_scc1 .LBB0_2777
	s_ashr_i32 s7, s6, 31
	s_lshl_b64 s[26:27], s[6:7], 1
	global_load_dwordx4 v[124:127], v[220:221], off
	global_load_dwordx4 v[128:131], v[222:223], off
	global_load_dwordx4 v[132:135], v[226:227], off
	v_lshl_add_u64 v[48:49], v[154:155], 0, s[26:27]
	v_lshl_add_u64 v[50:51], v[156:157], 0, s[26:27]
	global_load_dwordx4 v[140:143], v[48:49], off
	global_load_dwordx4 v[136:139], v[50:51], off
	v_lshl_add_u64 v[220:221], v[220:221], 0, v[228:229]
	v_lshl_add_u64 v[222:223], v[222:223], 0, v[230:231]
	v_lshl_add_u64 v[226:227], v[226:227], 0, v[232:233]
